# QKV epilogue reuses rotary table registers for the second head-half instead of reloading
# baseline (speedup 1.0000x reference)
; DI float shx(float v, int lane, int mask) { return __int_as_float(__builtin_amdgcn_ds_bpermute((lane ^ mask) << 2, __float_as_int(v))); }
; DI u32x4 pk8(const f32x4& v0, const f32x4& v1) { u32x4 w; w.x = cvt_pk_bf16(v0[0], v0[1]); w.y = cvt_pk_bf16(v0[2], v0[3]); w.z = cvt_pk_bf16(v1[0], v1[1]); w.w = cvt_pk_bf16(v1[2], v1[3]); return w; }
;   DI void epi(const Acc& acc, const Unit& u, int wr, int wc, int fr, int fq, LAS unsigned char* lds) const {
;     ...
;           for (int bj = 0; bj < 2; ++bj) {
;             f32x4 v0 = acc[ai][bj][m][0], v1 = acc[ai][bj][m][1];
;             if (rot) {
;               f32x4 o0, o1;
; #pragma unroll
;               for (int j = 0; j < 4; ++j) { o0[j] = shx(v0[j], fq * 16 + fr, 16); o1[j] = shx(v1[j], fq * 16 + fr, 16); }
;               if (fq < 2) {
;                 const f32x4 c0 = ldf4(cosA, (unsigned)pos * 32u), c1 = ldf4(cosA, (unsigned)pos * 32u + 16u);
;                 f32x4 s0 = ldf4(sinA, (unsigned)pos * 32u), s1 = ldf4(sinA, (unsigned)pos * 32u + 16u);
;                 if (fq == 0) { s0 = -s0; s1 = -s1; }
;                 v0 = v0 * c0 + o0 * s0; v1 = v1 * c1 + o1 * s1;
;               }
;             }
;             v0 *= sc; v1 *= sc;
;             {
;               const int hl = bj * 2 + (wc >> 1), head = isq ? u.pn * 4 + hl : hl, d0 = (wc & 1) * 32 + 8 * fq;
;               st16(isq ? q : k, (unsigned)((((head * 1024 + (row >> 5)) * 4 + (d0 >> 4)) * 64 + ((d0 >> 3) & 1) * 32 + (row & 31)) * 16), pk8(v0, v1)); }
.LBB0_275:
	s_lshl_b32 s23, s51, 2
	s_cmp_lt_i32 s51, 4
	s_cselect_b64 vcc, -1, 0
	s_and_b64 s[34:35], vcc, exec
	s_mov_b32 s34, 0xbe00000
	s_cselect_b32 s34, 0x7e00000, s34
	s_cselect_b32 s23, s23, 0
	s_add_u32 s0, s0, s34
	s_addc_u32 s1, s1, 0
	s_lshr_b32 s34, s2, 3
	s_and_b32 s34, s34, 0x3fffff8
	s_waitcnt lgkmcnt(0)
	v_mov_b32_e32 v140, 0x3e000000
	v_or_b32_e32 v141, s34, v162
	s_or_b32 s23, s23, s46
	v_cndmask_b32_e32 v140, 1.0, v140, vcc
	s_lshl_b32 s23, s23, 18
	v_lshlrev_b32_e32 v150, 6, v141
	v_pk_mul_f32 v[152:153], v[140:141], v[122:123] op_sel_hi:[0,1]
	v_pk_mul_f32 v[122:123], v[140:141], v[120:121] op_sel_hi:[0,1]
	v_add_u32_e32 v120, s23, v150
	v_or_b32_e32 v120, v120, v165
	v_pk_mul_f32 v[124:125], v[140:141], v[124:125] op_sel_hi:[0,1]
	v_lshlrev_b32_e32 v176, 4, v120
	v_cvt_pk_bf16_f32 v120, v124, v125
	v_lshl_add_u64 v[124:125], s[0:1], 0, v[176:177]
	v_pk_mul_f32 v[126:127], v[140:141], v[126:127] op_sel_hi:[0,1]
	v_cvt_pk_bf16_f32 v121, v126, v127
	v_cvt_pk_bf16_f32 v122, v122, v123
	v_cvt_pk_bf16_f32 v123, v152, v153
	global_store_dwordx4 v[124:125], v[120:123], off
	s_and_b64 vcc, exec, s[10:11]
	s_cbranch_vccnz .LBB0_279
	ds_bpermute_b32 v126, v164, v116
	ds_bpermute_b32 v122, v164, v112
	ds_bpermute_b32 v127, v164, v117
	ds_bpermute_b32 v123, v164, v113
	ds_bpermute_b32 v124, v164, v118
	ds_bpermute_b32 v120, v164, v114
	ds_bpermute_b32 v125, v164, v119
	ds_bpermute_b32 v121, v164, v115
	s_and_saveexec_b64 s[34:35], s[6:7]
	s_cbranch_execz .LBB0_278
	s_waitcnt lgkmcnt(0)
	v_pk_mul_f32 v[126:127], v[168:169], v[126:127]
	v_pk_mul_f32 v[124:125], v[170:171], v[124:125]
	v_pk_mul_f32 v[122:123], v[172:173], v[122:123]
	v_pk_mul_f32 v[120:121], v[174:175], v[120:121]
	v_pk_fma_f32 v[118:119], v[118:119], v[180:181], v[124:125]
	v_pk_fma_f32 v[116:117], v[116:117], v[178:179], v[126:127]
	v_pk_fma_f32 v[114:115], v[114:115], v[184:185], v[120:121]
	v_pk_fma_f32 v[112:113], v[112:113], v[182:183], v[122:123]

; DI float shx(float v, int lane, int mask) { return __int_as_float(__builtin_amdgcn_ds_bpermute((lane ^ mask) << 2, __float_as_int(v))); }
; DI u32x4 pk8(const f32x4& v0, const f32x4& v1) { u32x4 w; w.x = cvt_pk_bf16(v0[0], v0[1]); w.y = cvt_pk_bf16(v0[2], v0[3]); w.z = cvt_pk_bf16(v1[0], v1[1]); w.w = cvt_pk_bf16(v1[2], v1[3]); return w; }
;   DI void epi(const Acc& acc, const Unit& u, int wr, int wc, int fr, int fq, LAS unsigned char* lds) const {
;     ...
;           for (int bj = 0; bj < 2; ++bj) {
;             f32x4 v0 = acc[ai][bj][m][0], v1 = acc[ai][bj][m][1];
;             if (rot) {
;               f32x4 o0, o1;
; #pragma unroll
;               for (int j = 0; j < 4; ++j) { o0[j] = shx(v0[j], fq * 16 + fr, 16); o1[j] = shx(v1[j], fq * 16 + fr, 16); }
;               if (fq < 2) {
;                 const f32x4 c0 = ldf4(cosA, (unsigned)pos * 32u), c1 = ldf4(cosA, (unsigned)pos * 32u + 16u);
;                 f32x4 s0 = ldf4(sinA, (unsigned)pos * 32u), s1 = ldf4(sinA, (unsigned)pos * 32u + 16u);
;                 if (fq == 0) { s0 = -s0; s1 = -s1; }
;                 v0 = v0 * c0 + o0 * s0; v1 = v1 * c1 + o1 * s1;
;               }
;             }
;             v0 *= sc; v1 *= sc;
;             {
;               const int hl = bj * 2 + (wc >> 1), head = isq ? u.pn * 4 + hl : hl, d0 = (wc & 1) * 32 + 8 * fq;
;               st16(isq ? q : k, (unsigned)((((head * 1024 + (row >> 5)) * 4 + (d0 >> 4)) * 64 + ((d0 >> 3) & 1) * 32 + (row & 31)) * 16), pk8(v0, v1)); }
.LBB0_283:
	s_lshr_b32 s34, s53, 3
	s_and_b32 s34, s34, 0x3fffff8
	s_waitcnt lgkmcnt(0)
	v_or_b32_e32 v123, s34, v162
	v_pk_mul_f32 v[110:111], v[120:121], v[110:111]
	v_pk_mul_f32 v[124:125], v[120:121], v[106:107]
	v_lshlrev_b32_e32 v120, 6, v123
	v_and_or_b32 v122, v144, 31, v163
	v_pk_mul_f32 v[106:107], v[140:141], v[104:105]
	v_add_u32_e32 v104, s23, v120
	v_or_b32_e32 v104, v104, v122
	v_pk_mul_f32 v[108:109], v[140:141], v[108:109]
	v_lshlrev_b32_e32 v176, 4, v104
	v_cvt_pk_bf16_f32 v104, v108, v109
	v_lshl_add_u64 v[108:109], s[0:1], 0, v[176:177]
	v_cvt_pk_bf16_f32 v105, v110, v111
	v_cvt_pk_bf16_f32 v106, v106, v107
	v_cvt_pk_bf16_f32 v107, v124, v125
	global_store_dwordx4 v[108:109], v[104:107], off
	s_and_b64 vcc, exec, s[10:11]
	s_cbranch_vccnz .LBB0_287
	ds_bpermute_b32 v110, v164, v100
	ds_bpermute_b32 v106, v164, v96
	ds_bpermute_b32 v111, v164, v101
	ds_bpermute_b32 v107, v164, v97
	ds_bpermute_b32 v108, v164, v102
	ds_bpermute_b32 v104, v164, v98
	ds_bpermute_b32 v109, v164, v103
	ds_bpermute_b32 v105, v164, v99
	s_and_saveexec_b64 s[34:35], s[6:7]
	s_cbranch_execz .LBB0_286
	s_waitcnt lgkmcnt(0)
	v_pk_mul_f32 v[110:111], v[146:147], v[110:111]
	v_pk_mul_f32 v[108:109], v[148:149], v[108:109]
	v_pk_mul_f32 v[106:107], v[150:151], v[106:107]
	v_pk_mul_f32 v[104:105], v[152:153], v[104:105]
	v_pk_fma_f32 v[102:103], v[102:103], v[170:171], v[108:109]
	v_pk_fma_f32 v[100:101], v[100:101], v[168:169], v[110:111]
	v_pk_fma_f32 v[98:99], v[98:99], v[174:175], v[104:105]
	v_pk_fma_f32 v[96:97], v[96:97], v[172:173], v[106:107]

; DI float shx(float v, int lane, int mask) { return __int_as_float(__builtin_amdgcn_ds_bpermute((lane ^ mask) << 2, __float_as_int(v))); }
; DI u32x4 pk8(const f32x4& v0, const f32x4& v1) { u32x4 w; w.x = cvt_pk_bf16(v0[0], v0[1]); w.y = cvt_pk_bf16(v0[2], v0[3]); w.z = cvt_pk_bf16(v1[0], v1[1]); w.w = cvt_pk_bf16(v1[2], v1[3]); return w; }
;   DI void epi(const Acc& acc, const Unit& u, int wr, int wc, int fr, int fq, LAS unsigned char* lds) const {
;     ...
;           for (int bj = 0; bj < 2; ++bj) {
;             f32x4 v0 = acc[ai][bj][m][0], v1 = acc[ai][bj][m][1];
;             if (rot) {
;               f32x4 o0, o1;
; #pragma unroll
;               for (int j = 0; j < 4; ++j) { o0[j] = shx(v0[j], fq * 16 + fr, 16); o1[j] = shx(v1[j], fq * 16 + fr, 16); }
;               if (fq < 2) {
;                 const f32x4 c0 = ldf4(cosA, (unsigned)pos * 32u), c1 = ldf4(cosA, (unsigned)pos * 32u + 16u);
;                 f32x4 s0 = ldf4(sinA, (unsigned)pos * 32u), s1 = ldf4(sinA, (unsigned)pos * 32u + 16u);
;                 if (fq == 0) { s0 = -s0; s1 = -s1; }
;                 v0 = v0 * c0 + o0 * s0; v1 = v1 * c1 + o1 * s1;
;               }
;             }
;             v0 *= sc; v1 *= sc;
;             {
;               const int hl = bj * 2 + (wc >> 1), head = isq ? u.pn * 4 + hl : hl, d0 = (wc & 1) * 32 + 8 * fq;
;               st16(isq ? q : k, (unsigned)((((head * 1024 + (row >> 5)) * 4 + (d0 >> 4)) * 64 + ((d0 >> 3) & 1) * 32 + (row & 31)) * 16), pk8(v0, v1)); }
.LBB0_291:
	s_lshr_b32 s34, s53, 3
	s_and_b32 s34, s34, 0x3fffffc
	s_waitcnt lgkmcnt(0)
	v_or_b32_e32 v108, s34, v162
	v_pk_mul_f32 v[94:95], v[104:105], v[94:95]
	v_pk_mul_f32 v[106:107], v[104:105], v[90:91]
	v_lshlrev_b32_e32 v104, 6, v108
	v_pk_mul_f32 v[90:91], v[140:141], v[88:89]
	v_add_u32_e32 v88, s23, v104
	v_or_b32_e32 v88, v88, v165
	v_pk_mul_f32 v[92:93], v[140:141], v[92:93]
	v_lshlrev_b32_e32 v176, 4, v88
	v_cvt_pk_bf16_f32 v88, v92, v93
	v_lshl_add_u64 v[92:93], s[0:1], 0, v[176:177]
	v_cvt_pk_bf16_f32 v89, v94, v95
	v_cvt_pk_bf16_f32 v90, v90, v91
	v_cvt_pk_bf16_f32 v91, v106, v107
	global_store_dwordx4 v[92:93], v[88:91], off
	s_and_b64 vcc, exec, s[10:11]
	s_cbranch_vccnz .LBB0_295
	ds_bpermute_b32 v94, v164, v84
	ds_bpermute_b32 v90, v164, v80
	ds_bpermute_b32 v95, v164, v85
	ds_bpermute_b32 v91, v164, v81
	ds_bpermute_b32 v92, v164, v86
	ds_bpermute_b32 v88, v164, v82
	ds_bpermute_b32 v93, v164, v87
	ds_bpermute_b32 v89, v164, v83
	s_and_saveexec_b64 s[34:35], s[6:7]
	s_cbranch_execz .LBB0_294
	s_waitcnt lgkmcnt(0)
	v_pk_mul_f32 v[94:95], v[114:115], v[94:95]
	v_pk_mul_f32 v[92:93], v[116:117], v[92:93]
	v_pk_mul_f32 v[90:91], v[118:119], v[90:91]
	v_pk_mul_f32 v[88:89], v[120:121], v[88:89]
	v_pk_fma_f32 v[86:87], v[86:87], v[124:125], v[92:93]
	v_pk_fma_f32 v[84:85], v[84:85], v[122:123], v[94:95]
	v_pk_fma_f32 v[82:83], v[82:83], v[144:145], v[88:89]
	v_pk_fma_f32 v[80:81], v[80:81], v[142:143], v[90:91]

; DI float shx(float v, int lane, int mask) { return __int_as_float(__builtin_amdgcn_ds_bpermute((lane ^ mask) << 2, __float_as_int(v))); }
; DI u32x4 pk8(const f32x4& v0, const f32x4& v1) { u32x4 w; w.x = cvt_pk_bf16(v0[0], v0[1]); w.y = cvt_pk_bf16(v0[2], v0[3]); w.z = cvt_pk_bf16(v1[0], v1[1]); w.w = cvt_pk_bf16(v1[2], v1[3]); return w; }
;   DI void epi(const Acc& acc, const Unit& u, int wr, int wc, int fr, int fq, LAS unsigned char* lds) const {
;     ...
;           for (int bj = 0; bj < 2; ++bj) {
;             f32x4 v0 = acc[ai][bj][m][0], v1 = acc[ai][bj][m][1];
;             if (rot) {
;               f32x4 o0, o1;
; #pragma unroll
;               for (int j = 0; j < 4; ++j) { o0[j] = shx(v0[j], fq * 16 + fr, 16); o1[j] = shx(v1[j], fq * 16 + fr, 16); }
;               if (fq < 2) {
;                 const f32x4 c0 = ldf4(cosA, (unsigned)pos * 32u), c1 = ldf4(cosA, (unsigned)pos * 32u + 16u);
;                 f32x4 s0 = ldf4(sinA, (unsigned)pos * 32u), s1 = ldf4(sinA, (unsigned)pos * 32u + 16u);
;                 if (fq == 0) { s0 = -s0; s1 = -s1; }
;                 v0 = v0 * c0 + o0 * s0; v1 = v1 * c1 + o1 * s1;
;               }
;             }
;             v0 *= sc; v1 *= sc;
;             {
;               const int hl = bj * 2 + (wc >> 1), head = isq ? u.pn * 4 + hl : hl, d0 = (wc & 1) * 32 + 8 * fq;
;               st16(isq ? q : k, (unsigned)((((head * 1024 + (row >> 5)) * 4 + (d0 >> 4)) * 64 + ((d0 >> 3) & 1) * 32 + (row & 31)) * 16), pk8(v0, v1)); }
.LBB0_299:
	s_lshr_b32 s34, s52, 3
	s_and_b32 s34, s34, 0x3fffffc
	s_waitcnt lgkmcnt(0)
	v_or_b32_e32 v91, s34, v162
	v_pk_mul_f32 v[78:79], v[88:89], v[78:79]
	v_pk_mul_f32 v[92:93], v[88:89], v[74:75]
	v_lshlrev_b32_e32 v88, 6, v91
	v_and_or_b32 v90, v98, 31, v163
	v_pk_mul_f32 v[74:75], v[140:141], v[72:73]
	v_add_u32_e32 v72, s23, v88
	v_or_b32_e32 v72, v72, v90
	v_pk_mul_f32 v[76:77], v[140:141], v[76:77]
	v_lshlrev_b32_e32 v176, 4, v72
	v_cvt_pk_bf16_f32 v72, v76, v77
	v_lshl_add_u64 v[76:77], s[0:1], 0, v[176:177]
	v_cvt_pk_bf16_f32 v73, v78, v79
	v_cvt_pk_bf16_f32 v74, v74, v75
	v_cvt_pk_bf16_f32 v75, v92, v93
	global_store_dwordx4 v[76:77], v[72:75], off
	s_and_b64 vcc, exec, s[10:11]
	s_cbranch_vccnz .LBB0_303
	ds_bpermute_b32 v78, v164, v68
	ds_bpermute_b32 v74, v164, v64
	ds_bpermute_b32 v79, v164, v69
	ds_bpermute_b32 v75, v164, v65
	ds_bpermute_b32 v76, v164, v70
	ds_bpermute_b32 v72, v164, v66
	ds_bpermute_b32 v77, v164, v71
	ds_bpermute_b32 v73, v164, v67
	s_and_saveexec_b64 s[34:35], s[6:7]
	s_cbranch_execz .LBB0_302
	s_waitcnt lgkmcnt(0)
	v_pk_mul_f32 v[78:79], v[100:101], v[78:79]
	v_pk_mul_f32 v[76:77], v[102:103], v[76:77]
	v_pk_mul_f32 v[74:75], v[104:105], v[74:75]
	v_pk_mul_f32 v[72:73], v[106:107], v[72:73]
	v_pk_fma_f32 v[70:71], v[70:71], v[110:111], v[76:77]
	v_pk_fma_f32 v[68:69], v[68:69], v[108:109], v[78:79]
	v_pk_fma_f32 v[66:67], v[66:67], v[114:115], v[72:73]
	v_pk_fma_f32 v[64:65], v[64:65], v[112:113], v[74:75]

; DI float shx(float v, int lane, int mask) { return __int_as_float(__builtin_amdgcn_ds_bpermute((lane ^ mask) << 2, __float_as_int(v))); }
; DI u32x4 pk8(const f32x4& v0, const f32x4& v1) { u32x4 w; w.x = cvt_pk_bf16(v0[0], v0[1]); w.y = cvt_pk_bf16(v0[2], v0[3]); w.z = cvt_pk_bf16(v1[0], v1[1]); w.w = cvt_pk_bf16(v1[2], v1[3]); return w; }
;   DI void epi(const Acc& acc, const Unit& u, int wr, int wc, int fr, int fq, LAS unsigned char* lds) const {
;     ...
;           for (int bj = 0; bj < 2; ++bj) {
;             f32x4 v0 = acc[ai][bj][m][0], v1 = acc[ai][bj][m][1];
;             if (rot) {
;               f32x4 o0, o1;
; #pragma unroll
;               for (int j = 0; j < 4; ++j) { o0[j] = shx(v0[j], fq * 16 + fr, 16); o1[j] = shx(v1[j], fq * 16 + fr, 16); }
;               if (fq < 2) {
;                 const f32x4 c0 = ldf4(cosA, (unsigned)pos * 32u), c1 = ldf4(cosA, (unsigned)pos * 32u + 16u);
;                 f32x4 s0 = ldf4(sinA, (unsigned)pos * 32u), s1 = ldf4(sinA, (unsigned)pos * 32u + 16u);
;                 if (fq == 0) { s0 = -s0; s1 = -s1; }
;                 v0 = v0 * c0 + o0 * s0; v1 = v1 * c1 + o1 * s1;
;               }
;             }
;             v0 *= sc; v1 *= sc;
;             {
;               const int hl = bj * 2 + (wc >> 1), head = isq ? u.pn * 4 + hl : hl, d0 = (wc & 1) * 32 + 8 * fq;
;               st16(isq ? q : k, (unsigned)((((head * 1024 + (row >> 5)) * 4 + (d0 >> 4)) * 64 + ((d0 >> 3) & 1) * 32 + (row & 31)) * 16), pk8(v0, v1)); }
.LBB0_307:
	s_lshr_b32 s34, s52, 3
	s_and_b32 s34, s34, 0x3fffff8
	s_waitcnt lgkmcnt(0)
	v_or_b32_e32 v76, s34, v162
	v_pk_mul_f32 v[62:63], v[72:73], v[62:63]
	v_pk_mul_f32 v[74:75], v[72:73], v[58:59]
	v_lshlrev_b32_e32 v72, 6, v76
	v_pk_mul_f32 v[58:59], v[140:141], v[56:57]
	v_add_u32_e32 v56, s23, v72
	v_or_b32_e32 v56, v56, v165
	v_pk_mul_f32 v[60:61], v[140:141], v[60:61]
	v_lshlrev_b32_e32 v176, 4, v56
	v_cvt_pk_bf16_f32 v56, v60, v61
	v_lshl_add_u64 v[60:61], s[0:1], 0, v[176:177]
	v_cvt_pk_bf16_f32 v57, v62, v63
	v_cvt_pk_bf16_f32 v58, v58, v59
	v_cvt_pk_bf16_f32 v59, v74, v75
	global_store_dwordx4 v[60:61], v[56:59], off
	s_and_b64 vcc, exec, s[10:11]
	s_cbranch_vccnz .LBB0_311
	ds_bpermute_b32 v62, v164, v52
	ds_bpermute_b32 v58, v164, v48
	ds_bpermute_b32 v63, v164, v53
	ds_bpermute_b32 v59, v164, v49
	ds_bpermute_b32 v60, v164, v54
	ds_bpermute_b32 v56, v164, v50
	ds_bpermute_b32 v61, v164, v55
	ds_bpermute_b32 v57, v164, v51
	s_and_saveexec_b64 s[34:35], s[6:7]
	s_cbranch_execz .LBB0_310
	s_waitcnt lgkmcnt(0)
	v_pk_mul_f32 v[62:63], v[82:83], v[62:63]
	v_pk_mul_f32 v[60:61], v[84:85], v[60:61]
	v_pk_mul_f32 v[58:59], v[86:87], v[58:59]
	v_pk_mul_f32 v[56:57], v[88:89], v[56:57]
	v_pk_fma_f32 v[54:55], v[54:55], v[92:93], v[60:61]
	v_pk_fma_f32 v[52:53], v[52:53], v[90:91], v[62:63]
	v_pk_fma_f32 v[50:51], v[50:51], v[96:97], v[56:57]
	v_pk_fma_f32 v[48:49], v[48:49], v[94:95], v[58:59]

; DI float shx(float v, int lane, int mask) { return __int_as_float(__builtin_amdgcn_ds_bpermute((lane ^ mask) << 2, __float_as_int(v))); }
; DI u32x4 pk8(const f32x4& v0, const f32x4& v1) { u32x4 w; w.x = cvt_pk_bf16(v0[0], v0[1]); w.y = cvt_pk_bf16(v0[2], v0[3]); w.z = cvt_pk_bf16(v1[0], v1[1]); w.w = cvt_pk_bf16(v1[2], v1[3]); return w; }
;   DI void epi(const Acc& acc, const Unit& u, int wr, int wc, int fr, int fq, LAS unsigned char* lds) const {
;     ...
;           for (int bj = 0; bj < 2; ++bj) {
;             f32x4 v0 = acc[ai][bj][m][0], v1 = acc[ai][bj][m][1];
;             if (rot) {
;               f32x4 o0, o1;
; #pragma unroll
;               for (int j = 0; j < 4; ++j) { o0[j] = shx(v0[j], fq * 16 + fr, 16); o1[j] = shx(v1[j], fq * 16 + fr, 16); }
;               if (fq < 2) {
;                 const f32x4 c0 = ldf4(cosA, (unsigned)pos * 32u), c1 = ldf4(cosA, (unsigned)pos * 32u + 16u);
;                 f32x4 s0 = ldf4(sinA, (unsigned)pos * 32u), s1 = ldf4(sinA, (unsigned)pos * 32u + 16u);
;                 if (fq == 0) { s0 = -s0; s1 = -s1; }
;                 v0 = v0 * c0 + o0 * s0; v1 = v1 * c1 + o1 * s1;
;               }
;             }
;             v0 *= sc; v1 *= sc;
;             {
;               const int hl = bj * 2 + (wc >> 1), head = isq ? u.pn * 4 + hl : hl, d0 = (wc & 1) * 32 + 8 * fq;
;               st16(isq ? q : k, (unsigned)((((head * 1024 + (row >> 5)) * 4 + (d0 >> 4)) * 64 + ((d0 >> 3) & 1) * 32 + (row & 31)) * 16), pk8(v0, v1)); }
.LBB0_315:
	s_lshr_b32 s34, s52, 3
	s_and_b32 s34, s34, 0x3fffff8
	s_waitcnt lgkmcnt(0)
	v_or_b32_e32 v59, s34, v162
	v_pk_mul_f32 v[46:47], v[56:57], v[46:47]
	v_pk_mul_f32 v[60:61], v[56:57], v[42:43]
	v_lshlrev_b32_e32 v56, 6, v59
	v_and_or_b32 v58, v66, 31, v163
	v_pk_mul_f32 v[42:43], v[140:141], v[40:41]
	v_add_u32_e32 v40, s23, v56
	v_or_b32_e32 v40, v40, v58
	v_pk_mul_f32 v[44:45], v[140:141], v[44:45]
	v_lshlrev_b32_e32 v176, 4, v40
	v_cvt_pk_bf16_f32 v40, v44, v45
	v_lshl_add_u64 v[44:45], s[0:1], 0, v[176:177]
	v_cvt_pk_bf16_f32 v41, v46, v47
	v_cvt_pk_bf16_f32 v42, v42, v43
	v_cvt_pk_bf16_f32 v43, v60, v61
	global_store_dwordx4 v[44:45], v[40:43], off
	s_and_b64 vcc, exec, s[10:11]
	s_cbranch_vccnz .LBB0_319
	ds_bpermute_b32 v46, v164, v36
	ds_bpermute_b32 v42, v164, v32
	ds_bpermute_b32 v47, v164, v37
	ds_bpermute_b32 v43, v164, v33
	ds_bpermute_b32 v44, v164, v38
	ds_bpermute_b32 v40, v164, v34
	ds_bpermute_b32 v45, v164, v39
	ds_bpermute_b32 v41, v164, v35
	s_and_saveexec_b64 s[34:35], s[6:7]
	s_cbranch_execz .LBB0_318
	s_waitcnt lgkmcnt(0)
	v_pk_mul_f32 v[46:47], v[68:69], v[46:47]
	v_pk_mul_f32 v[44:45], v[70:71], v[44:45]
	v_pk_mul_f32 v[42:43], v[72:73], v[42:43]
	v_pk_mul_f32 v[40:41], v[74:75], v[40:41]
	v_pk_fma_f32 v[38:39], v[38:39], v[78:79], v[44:45]
	v_pk_fma_f32 v[36:37], v[36:37], v[76:77], v[46:47]
	v_pk_fma_f32 v[34:35], v[34:35], v[82:83], v[40:41]
	v_pk_fma_f32 v[32:33], v[32:33], v[80:81], v[42:43]

; DI float shx(float v, int lane, int mask) { return __int_as_float(__builtin_amdgcn_ds_bpermute((lane ^ mask) << 2, __float_as_int(v))); }
; DI u32x4 pk8(const f32x4& v0, const f32x4& v1) { u32x4 w; w.x = cvt_pk_bf16(v0[0], v0[1]); w.y = cvt_pk_bf16(v0[2], v0[3]); w.z = cvt_pk_bf16(v1[0], v1[1]); w.w = cvt_pk_bf16(v1[2], v1[3]); return w; }
;   DI void epi(const Acc& acc, const Unit& u, int wr, int wc, int fr, int fq, LAS unsigned char* lds) const {
;     ...
;           for (int bj = 0; bj < 2; ++bj) {
;             f32x4 v0 = acc[ai][bj][m][0], v1 = acc[ai][bj][m][1];
;             if (rot) {
;               f32x4 o0, o1;
; #pragma unroll
;               for (int j = 0; j < 4; ++j) { o0[j] = shx(v0[j], fq * 16 + fr, 16); o1[j] = shx(v1[j], fq * 16 + fr, 16); }
;               if (fq < 2) {
;                 const f32x4 c0 = ldf4(cosA, (unsigned)pos * 32u), c1 = ldf4(cosA, (unsigned)pos * 32u + 16u);
;                 f32x4 s0 = ldf4(sinA, (unsigned)pos * 32u), s1 = ldf4(sinA, (unsigned)pos * 32u + 16u);
;                 if (fq == 0) { s0 = -s0; s1 = -s1; }
;                 v0 = v0 * c0 + o0 * s0; v1 = v1 * c1 + o1 * s1;
;               }
;             }
;             v0 *= sc; v1 *= sc;
;             {
;               const int hl = bj * 2 + (wc >> 1), head = isq ? u.pn * 4 + hl : hl, d0 = (wc & 1) * 32 + 8 * fq;
;               st16(isq ? q : k, (unsigned)((((head * 1024 + (row >> 5)) * 4 + (d0 >> 4)) * 64 + ((d0 >> 3) & 1) * 32 + (row & 31)) * 16), pk8(v0, v1)); }
.LBB0_323:
	s_lshr_b32 s34, s52, 3
	s_and_b32 s34, s34, 0x3fffffc
	s_waitcnt lgkmcnt(0)
	v_or_b32_e32 v44, s34, v162
	v_pk_mul_f32 v[30:31], v[40:41], v[30:31]
	v_pk_mul_f32 v[42:43], v[40:41], v[26:27]
	v_lshlrev_b32_e32 v40, 6, v44
	v_pk_mul_f32 v[26:27], v[140:141], v[24:25]
	v_add_u32_e32 v24, s23, v40
	v_or_b32_e32 v24, v24, v165
	v_pk_mul_f32 v[28:29], v[140:141], v[28:29]
	v_lshlrev_b32_e32 v176, 4, v24
	v_cvt_pk_bf16_f32 v24, v28, v29
	v_lshl_add_u64 v[28:29], s[0:1], 0, v[176:177]
	v_cvt_pk_bf16_f32 v25, v30, v31
	v_cvt_pk_bf16_f32 v26, v26, v27
	v_cvt_pk_bf16_f32 v27, v42, v43
	global_store_dwordx4 v[28:29], v[24:27], off
	s_and_b64 vcc, exec, s[10:11]
	s_cbranch_vccnz .LBB0_327
	ds_bpermute_b32 v30, v164, v20
	ds_bpermute_b32 v26, v164, v16
	ds_bpermute_b32 v31, v164, v21
	ds_bpermute_b32 v27, v164, v17
	ds_bpermute_b32 v28, v164, v22
	ds_bpermute_b32 v24, v164, v18
	ds_bpermute_b32 v29, v164, v23
	ds_bpermute_b32 v25, v164, v19
	s_and_saveexec_b64 s[34:35], s[6:7]
	s_cbranch_execz .LBB0_326
	s_waitcnt lgkmcnt(0)
	v_pk_mul_f32 v[30:31], v[50:51], v[30:31]
	v_pk_mul_f32 v[28:29], v[52:53], v[28:29]
	v_pk_mul_f32 v[26:27], v[54:55], v[26:27]
	v_pk_mul_f32 v[24:25], v[56:57], v[24:25]
	v_pk_fma_f32 v[22:23], v[22:23], v[60:61], v[28:29]
	v_pk_fma_f32 v[20:21], v[20:21], v[58:59], v[30:31]
	v_pk_fma_f32 v[18:19], v[18:19], v[64:65], v[24:25]
	v_pk_fma_f32 v[16:17], v[16:17], v[62:63], v[26:27]

; DI float shx(float v, int lane, int mask) { return __int_as_float(__builtin_amdgcn_ds_bpermute((lane ^ mask) << 2, __float_as_int(v))); }
; DI u32x4 pk8(const f32x4& v0, const f32x4& v1) { u32x4 w; w.x = cvt_pk_bf16(v0[0], v0[1]); w.y = cvt_pk_bf16(v0[2], v0[3]); w.z = cvt_pk_bf16(v1[0], v1[1]); w.w = cvt_pk_bf16(v1[2], v1[3]); return w; }
;   DI void epi(const Acc& acc, const Unit& u, int wr, int wc, int fr, int fq, LAS unsigned char* lds) const {
;     ...
;           for (int bj = 0; bj < 2; ++bj) {
;             f32x4 v0 = acc[ai][bj][m][0], v1 = acc[ai][bj][m][1];
;             if (rot) {
;               f32x4 o0, o1;
; #pragma unroll
;               for (int j = 0; j < 4; ++j) { o0[j] = shx(v0[j], fq * 16 + fr, 16); o1[j] = shx(v1[j], fq * 16 + fr, 16); }
;               if (fq < 2) {
;                 const f32x4 c0 = ldf4(cosA, (unsigned)pos * 32u), c1 = ldf4(cosA, (unsigned)pos * 32u + 16u);
;                 f32x4 s0 = ldf4(sinA, (unsigned)pos * 32u), s1 = ldf4(sinA, (unsigned)pos * 32u + 16u);
;                 if (fq == 0) { s0 = -s0; s1 = -s1; }
;                 v0 = v0 * c0 + o0 * s0; v1 = v1 * c1 + o1 * s1;
;               }
;             }
;             v0 *= sc; v1 *= sc;
;             {
;               const int hl = bj * 2 + (wc >> 1), head = isq ? u.pn * 4 + hl : hl, d0 = (wc & 1) * 32 + 8 * fq;
;               st16(isq ? q : k, (unsigned)((((head * 1024 + (row >> 5)) * 4 + (d0 >> 4)) * 64 + ((d0 >> 3) & 1) * 32 + (row & 31)) * 16), pk8(v0, v1)); }
.LBB0_331:
	s_lshr_b32 s2, s2, 3
	s_and_b32 s2, s2, 0x3fffffc
	s_waitcnt lgkmcnt(0)
	v_or_b32_e32 v27, s2, v162
	v_pk_mul_f32 v[14:15], v[24:25], v[14:15]
	v_pk_mul_f32 v[28:29], v[24:25], v[10:11]
	v_lshlrev_b32_e32 v24, 6, v27
	v_and_or_b32 v26, v34, 31, v163
	v_pk_mul_f32 v[10:11], v[140:141], v[8:9]
	v_add_u32_e32 v8, s23, v24
	v_or_b32_e32 v8, v8, v26
	v_pk_mul_f32 v[12:13], v[140:141], v[12:13]
	v_lshlrev_b32_e32 v176, 4, v8
	v_cvt_pk_bf16_f32 v8, v12, v13
	v_lshl_add_u64 v[12:13], s[0:1], 0, v[176:177]
	v_cvt_pk_bf16_f32 v9, v14, v15
	v_cvt_pk_bf16_f32 v10, v10, v11
	v_cvt_pk_bf16_f32 v11, v28, v29
	global_store_dwordx4 v[12:13], v[8:11], off
	s_and_b64 vcc, exec, s[10:11]
	s_cbranch_vccnz .LBB0_335
	ds_bpermute_b32 v14, v164, v4
	ds_bpermute_b32 v10, v164, v0
	ds_bpermute_b32 v15, v164, v5
	ds_bpermute_b32 v11, v164, v1
	ds_bpermute_b32 v12, v164, v6
	ds_bpermute_b32 v8, v164, v2
	ds_bpermute_b32 v13, v164, v7
	ds_bpermute_b32 v9, v164, v3
	s_and_saveexec_b64 s[4:5], s[6:7]
	s_cbranch_execz .LBB0_334
	s_waitcnt lgkmcnt(0)
	v_pk_mul_f32 v[14:15], v[36:37], v[14:15]
	v_pk_mul_f32 v[12:13], v[38:39], v[12:13]
	v_pk_mul_f32 v[10:11], v[40:41], v[10:11]
	v_pk_mul_f32 v[8:9], v[42:43], v[8:9]
	v_pk_fma_f32 v[6:7], v[6:7], v[46:47], v[12:13]
	v_pk_fma_f32 v[4:5], v[4:5], v[44:45], v[14:15]
	v_pk_fma_f32 v[2:3], v[2:3], v[50:51], v[8:9]
	v_pk_fma_f32 v[0:1], v[0:1], v[48:49], v[10:11]
